# W1 GEMM epilogue: v_permlane16_swap pairs -> 16-byte bf16 stores (two global_store_dwordx4 per 16-row group instead of four dwordx2)
# speedup vs baseline: 1.0152x; 1.0152x over previous
; #define MFMA16(a, b, c) __builtin_amdgcn_mfma_f32_16x16x32_bf16((a), (b), (c), 0, 0, 0)
; template <class Epi>
; DEVI void gemm_tile256b(const bf16_t* __restrict__ A, int lda, const bf16_t* __restrict__ Bt, int K,
;                         int m0, int n0, char* smem, Epi epi) {
;     ...
;   for (int kt = 0; kt < nk; ++kt) {
;     const char* base = smem + (kt & 1) * 32768;
;     const bool more = kt + 1 < nk;
;     if (more) {
; #pragma unroll
;       for (int i = 0; i < 8; ++i) ra[i] = *(const u32x4*)(ag + (size_t)(i * 32) * lda + (kt + 1) * 64);
;     }
; #pragma unroll
;     for (int i = 0; i < 4; ++i) b1[i] = *(const bf16x8*)(bp + ((size_t)i * kb32 + kt * 2 + 1) * 512);
;     {
;       bf16x8 af[8];
; #pragma unroll
;       for (int i = 0; i < 8; ++i) af[i] = *(const bf16x8*)(base + a_rd + i * 2048);
; #pragma unroll
;       for (int mi = 0; mi < 8; ++mi)
; #pragma unroll
;         for (int ni = 0; ni < 4; ++ni) acc[mi][ni] = MFMA16(b0[ni], af[mi], acc[mi][ni]);
;     }
;     if (more) {
; #pragma unroll
;       for (int i = 0; i < 4; ++i) b0[i] = *(const bf16x8*)(bp + ((size_t)i * kb32 + kt * 2 + 2) * 512);
;     }
;     {
;       bf16x8 af[8];
; #pragma unroll
;       for (int i = 0; i < 8; ++i) af[i] = *(const bf16x8*)(base + ((a_rd + i * 2048) ^ 64));
; #pragma unroll
;       for (int mi = 0; mi < 8; ++mi)
; #pragma unroll
;         for (int ni = 0; ni < 4; ++ni) acc[mi][ni] = MFMA16(b1[ni], af[mi], acc[mi][ni]);
;     }
;     if (more) {
;       char* nb = smem + ((kt + 1) & 1) * 32768 + lds_w;
; #pragma unroll
;       for (int i = 0; i < 8; ++i) *(u32x4*)(nb + i * 4096) = ra[i];
;     }
;     __syncthreads();
.LBB0_1873:
	s_add_i32 s10, s1, 0xffff8000
	s_and_b32 s10, s10, 0x8000
	s_add_i32 s10, s10, 32
	v_add_u32_e32 v0, s10, v173
	ds_read_b128 v[146:149], v0
	ds_read_b128 v[150:153], v0 offset:2048
	v_lshl_add_u64 v[154:155], v[164:165], 0, s[28:29]
	s_mov_b32 s11, 0x2a80000
	v_add_co_u32_e32 v156, vcc, s11, v154
	s_waitcnt vmcnt(3) lgkmcnt(1)
	v_mfma_f32_16x16x32_bf16 v[134:137], v[10:13], v[146:149], v[134:137]
	v_addc_co_u32_e32 v157, vcc, 0, v155, vcc
	s_mov_b32 s11, 0x2a88000
	s_waitcnt vmcnt(2)
	v_mfma_f32_16x16x32_bf16 v[130:133], v[14:17], v[146:149], v[130:133]
	v_add_co_u32_e32 v158, vcc, s11, v154
	s_mov_b32 s11, 0x2a90000
	s_waitcnt vmcnt(1)
	v_mfma_f32_16x16x32_bf16 v[126:129], v[6:9], v[146:149], v[126:129]
	v_addc_co_u32_e32 v159, vcc, 0, v155, vcc
	v_add_co_u32_e32 v160, vcc, s11, v154
	s_waitcnt vmcnt(0)
	v_mfma_f32_16x16x32_bf16 v[122:125], v[2:5], v[146:149], v[122:125]
	v_addc_co_u32_e32 v161, vcc, 0, v155, vcc
	s_mov_b32 s11, 0x2a98000
	s_waitcnt lgkmcnt(0)
	v_mfma_f32_16x16x32_bf16 v[114:117], v[10:13], v[150:153], v[114:117]
	v_add_co_u32_e32 v182, vcc, s11, v154
	v_mfma_f32_16x16x32_bf16 v[110:113], v[14:17], v[150:153], v[110:113]
	v_addc_co_u32_e32 v183, vcc, 0, v155, vcc
	v_mfma_f32_16x16x32_bf16 v[106:109], v[6:9], v[150:153], v[106:109]
	s_nop 0
	v_mfma_f32_16x16x32_bf16 v[102:105], v[2:5], v[150:153], v[102:105]
	ds_read_b128 v[146:149], v0 offset:4096
	ds_read_b128 v[150:153], v0 offset:6144
	s_waitcnt lgkmcnt(1)
	v_mfma_f32_16x16x32_bf16 v[98:101], v[10:13], v[146:149], v[98:101]
	v_lshl_add_u64 v[164:165], v[164:165], 0, s[64:65]
	v_mfma_f32_16x16x32_bf16 v[94:97], v[14:17], v[146:149], v[94:97]
	v_mfma_f32_16x16x32_bf16 v[86:89], v[6:9], v[146:149], v[86:89]
	s_nop 0
	v_mfma_f32_16x16x32_bf16 v[82:85], v[2:5], v[146:149], v[82:85]
	s_nop 0
	s_waitcnt lgkmcnt(0)
	v_mfma_f32_16x16x32_bf16 v[74:77], v[10:13], v[150:153], v[74:77]
	v_mfma_f32_16x16x32_bf16 v[70:73], v[14:17], v[150:153], v[70:73]
	s_nop 0
	v_lshl_add_u64 v[166:167], v[166:167], 0, s[60:61]
	v_mfma_f32_16x16x32_bf16 v[62:65], v[6:9], v[150:153], v[62:65]
	v_mfma_f32_16x16x32_bf16 v[66:69], v[2:5], v[150:153], v[66:69]
	ds_read_b128 v[146:149], v0 offset:8192
	ds_read_b128 v[150:153], v0 offset:10240
	s_waitcnt lgkmcnt(1)
	v_mfma_f32_16x16x32_bf16 v[46:49], v[10:13], v[146:149], v[46:49]
	v_mfma_f32_16x16x32_bf16 v[50:53], v[14:17], v[146:149], v[50:53]
	v_mfma_f32_16x16x32_bf16 v[58:61], v[6:9], v[146:149], v[58:61]
	v_mfma_f32_16x16x32_bf16 v[54:57], v[2:5], v[146:149], v[54:57]
	s_waitcnt lgkmcnt(0)
	v_mfma_f32_16x16x32_bf16 v[26:29], v[10:13], v[150:153], v[26:29]
	v_mfma_f32_16x16x32_bf16 v[22:25], v[14:17], v[150:153], v[22:25]
	v_mfma_f32_16x16x32_bf16 v[18:21], v[6:9], v[150:153], v[18:21]
	v_mfma_f32_16x16x32_bf16 v[42:45], v[2:5], v[150:153], v[42:45]
	ds_read_b128 v[146:149], v0 offset:12288
	ds_read_b128 v[150:153], v0 offset:14336
	v_add_u32_e32 v0, s10, v171
	s_and_b32 s10, s1, 0x8000
	s_waitcnt lgkmcnt(1)
	v_mfma_f32_16x16x32_bf16 v[34:37], v[10:13], v[146:149], v[34:37]
	s_add_i32 s1, s1, 0x8000
	s_cmp_eq_u32 s1, 0x80000
	v_mfma_f32_16x16x32_bf16 v[38:41], v[14:17], v[146:149], v[38:41]
	v_mfma_f32_16x16x32_bf16 v[30:33], v[6:9], v[146:149], v[30:33]
	v_mfma_f32_16x16x32_bf16 v[142:145], v[2:5], v[146:149], v[142:145]
	global_load_dwordx4 v[146:149], v[156:157], off offset:1024
	ds_read_b128 v[174:177], v0
	ds_read_b128 v[178:181], v0 offset:2048
	s_waitcnt lgkmcnt(2)
	v_mfma_f32_16x16x32_bf16 v[138:141], v[10:13], v[150:153], v[138:141]
	global_load_dwordx4 v[10:13], v[156:157], off offset:2048
	v_mfma_f32_16x16x32_bf16 v[118:121], v[14:17], v[150:153], v[118:121]
	v_mfma_f32_16x16x32_bf16 v[90:93], v[6:9], v[150:153], v[90:93]
	v_mfma_f32_16x16x32_bf16 v[78:81], v[2:5], v[150:153], v[78:81]
	global_load_dwordx4 v[150:153], v[158:159], off offset:1024
	global_load_dwordx4 v[14:17], v[158:159], off offset:2048
	global_load_dwordx4 v[154:157], v[160:161], off offset:1024
	global_load_dwordx4 v[6:9], v[160:161], off offset:2048
	s_nop 0
	global_load_dwordx4 v[158:161], v[182:183], off offset:1024
	global_load_dwordx4 v[2:5], v[182:183], off offset:2048
	v_lshrrev_b32_e32 v195, 6, v206
	v_lshl_add_u64 v[190:191], v[166:167], 0, s[28:29]
	v_lshrrev_b32_e32 v194, 3, v206
	v_readfirstlane_b32 s99, v195
	v_and_b32_e32 v194, 7, v194
	s_and_b32 s98, s1, 0x8000
	s_xor_b32 s98, s98, 0x8000
	v_lshlrev_b32_e32 v194, 4, v194
	s_lshl_b32 s99, s99, 10
	v_xor_b32_e32 v190, v194, v190
	s_add_u32 s98, s98, s99
	s_add_u32 s98, s98, 32
	s_mov_b32 s101, 0
	s_mov_b32 s100, 0x0
	v_lshl_add_u64 v[192:193], v[190:191], 0, s[100:101]
	s_mov_b32 m0, s98
	s_nop 0
	global_load_lds_dwordx4 v[192:193], off
	s_add_u32 s100, s54, 0x0
	v_lshl_add_u64 v[192:193], v[190:191], 0, s[100:101]
	s_add_u32 m0, s98, 0x1000
	s_nop 0
	global_load_lds_dwordx4 v[192:193], off
	s_add_u32 s100, s53, 0x0
	v_lshl_add_u64 v[192:193], v[190:191], 0, s[100:101]
	s_add_u32 m0, s98, 0x2000
	s_nop 0
	global_load_lds_dwordx4 v[192:193], off
	s_add_u32 s100, s52, 0x0
	v_lshl_add_u64 v[192:193], v[190:191], 0, s[100:101]
	s_add_u32 m0, s98, 0x3000
	s_nop 0
	global_load_lds_dwordx4 v[192:193], off
	s_add_u32 s100, s56, 0x0
	v_lshl_add_u64 v[192:193], v[190:191], 0, s[100:101]
	s_add_u32 m0, s98, 0x4000
	s_nop 0
	global_load_lds_dwordx4 v[192:193], off
	s_add_u32 s100, s57, 0x0
	v_lshl_add_u64 v[192:193], v[190:191], 0, s[100:101]
	s_add_u32 m0, s98, 0x5000
	s_nop 0
	global_load_lds_dwordx4 v[192:193], off
	s_add_u32 s100, s3, 0x0
	v_lshl_add_u64 v[192:193], v[190:191], 0, s[100:101]
	s_add_u32 m0, s98, 0x6000
	s_nop 0
	global_load_lds_dwordx4 v[192:193], off
	s_add_u32 s100, s19, 0x0
	v_lshl_add_u64 v[192:193], v[190:191], 0, s[100:101]
	s_add_u32 m0, s98, 0x7000
	s_nop 0
	global_load_lds_dwordx4 v[192:193], off
	s_waitcnt vmcnt(15) lgkmcnt(1)
; #define MFMA16(a, b, c) __builtin_amdgcn_mfma_f32_16x16x32_bf16((a), (b), (c), 0, 0, 0)
; template <class Epi>
; DEVI void gemm_tile256b(const bf16_t* __restrict__ A, int lda, const bf16_t* __restrict__ Bt, int K,
;                         int m0, int n0, char* smem, Epi epi) {
;     ...
;     {
;       bf16x8 af[8];
; #pragma unroll
;       for (int i = 0; i < 8; ++i) af[i] = *(const bf16x8*)(base + ((a_rd + i * 2048) ^ 64));
; #pragma unroll
;       for (int mi = 0; mi < 8; ++mi)
; #pragma unroll
;         for (int ni = 0; ni < 4; ++ni) acc[mi][ni] = MFMA16(b1[ni], af[mi], acc[mi][ni]);
;     }
;     if (more) {
;       char* nb = smem + ((kt + 1) & 1) * 32768 + lds_w;
; #pragma unroll
;       for (int i = 0; i < 8; ++i) *(u32x4*)(nb + i * 4096) = ra[i];
;     }
;     __syncthreads();
;   }
; #pragma unroll
;   for (int mi = 0; mi < 8; ++mi)
; #pragma unroll
;     for (int ni = 0; ni < 4; ++ni)
;       epi(m0 + wm * 128 + mi * 16 + l15, n0 + wn * 64 + ni * 16 + quad * 4, acc[mi][ni]);
	v_mfma_f32_16x16x32_bf16 v[134:137], v[146:149], v[174:177], v[134:137]
	s_waitcnt vmcnt(13)
	v_mfma_f32_16x16x32_bf16 v[130:133], v[150:153], v[174:177], v[130:133]
	s_waitcnt vmcnt(11)
	v_mfma_f32_16x16x32_bf16 v[126:129], v[154:157], v[174:177], v[126:129]
	s_waitcnt vmcnt(9)
	v_mfma_f32_16x16x32_bf16 v[122:125], v[158:161], v[174:177], v[122:125]
	s_waitcnt lgkmcnt(0)
	v_mfma_f32_16x16x32_bf16 v[114:117], v[146:149], v[178:181], v[114:117]
	v_mfma_f32_16x16x32_bf16 v[110:113], v[150:153], v[178:181], v[110:113]
	v_mfma_f32_16x16x32_bf16 v[106:109], v[154:157], v[178:181], v[106:109]
	v_mfma_f32_16x16x32_bf16 v[102:105], v[158:161], v[178:181], v[102:105]
	ds_read_b128 v[174:177], v0 offset:4096
	ds_read_b128 v[178:181], v0 offset:6144
	s_waitcnt lgkmcnt(1)
	v_mfma_f32_16x16x32_bf16 v[98:101], v[146:149], v[174:177], v[98:101]
	v_mfma_f32_16x16x32_bf16 v[94:97], v[150:153], v[174:177], v[94:97]
	v_mfma_f32_16x16x32_bf16 v[86:89], v[154:157], v[174:177], v[86:89]
	v_mfma_f32_16x16x32_bf16 v[82:85], v[158:161], v[174:177], v[82:85]
	s_waitcnt lgkmcnt(0)
	v_mfma_f32_16x16x32_bf16 v[74:77], v[146:149], v[178:181], v[74:77]
	v_mfma_f32_16x16x32_bf16 v[70:73], v[150:153], v[178:181], v[70:73]
	v_mfma_f32_16x16x32_bf16 v[62:65], v[154:157], v[178:181], v[62:65]
	v_mfma_f32_16x16x32_bf16 v[66:69], v[158:161], v[178:181], v[66:69]
	ds_read_b128 v[178:181], v0 offset:8192
	ds_read_b128 v[182:185], v0 offset:10240
	s_waitcnt lgkmcnt(1)
	v_mfma_f32_16x16x32_bf16 v[46:49], v[146:149], v[178:181], v[46:49]
	v_mfma_f32_16x16x32_bf16 v[50:53], v[150:153], v[178:181], v[50:53]
	v_mfma_f32_16x16x32_bf16 v[58:61], v[154:157], v[178:181], v[58:61]
	v_mfma_f32_16x16x32_bf16 v[54:57], v[158:161], v[178:181], v[54:57]
	s_waitcnt lgkmcnt(0)
	v_mfma_f32_16x16x32_bf16 v[26:29], v[146:149], v[182:185], v[26:29]
	v_mfma_f32_16x16x32_bf16 v[22:25], v[150:153], v[182:185], v[22:25]
	v_mfma_f32_16x16x32_bf16 v[18:21], v[154:157], v[182:185], v[18:21]
	v_mfma_f32_16x16x32_bf16 v[42:45], v[158:161], v[182:185], v[42:45]
	ds_read_b128 v[178:181], v0 offset:12288
	ds_read_b128 v[182:185], v0 offset:14336
	s_nop 0
	s_nop 0
	s_nop 0
	s_nop 0
	s_nop 0
	s_waitcnt lgkmcnt(1)
	v_mfma_f32_16x16x32_bf16 v[34:37], v[146:149], v[178:181], v[34:37]
	v_mfma_f32_16x16x32_bf16 v[38:41], v[150:153], v[178:181], v[38:41]
	v_mfma_f32_16x16x32_bf16 v[30:33], v[154:157], v[178:181], v[30:33]
	s_waitcnt vmcnt(0) lgkmcnt(0)
	s_barrier
	v_mfma_f32_16x16x32_bf16 v[142:145], v[158:161], v[178:181], v[142:145]
	v_mfma_f32_16x16x32_bf16 v[138:141], v[146:149], v[182:185], v[138:141]
	v_mfma_f32_16x16x32_bf16 v[118:121], v[150:153], v[182:185], v[118:121]
	v_mfma_f32_16x16x32_bf16 v[90:93], v[154:157], v[182:185], v[90:93]
	v_mfma_f32_16x16x32_bf16 v[78:81], v[158:161], v[182:185], v[78:81]
	s_cmp_eq_u32 s1, 0x80000
	s_cbranch_scc0 .LBB0_1873
	v_and_b32_e32 v236, 16, v206
	v_lshrrev_b32_e32 v237, 1, v236
	v_add_u32_e32 v236, v236, v237
	v_mov_b32_e32 v237, 0
	v_add_u32_e32 v0, 32, v173
	ds_read_b128 v[146:149], v0 offset:32768
	s_movk_i32 s1, 0x7000
	s_waitcnt lgkmcnt(0)
	v_mfma_f32_16x16x32_bf16 v[134:137], v[10:13], v[146:149], v[134:137]
	v_mfma_f32_16x16x32_bf16 v[130:133], v[14:17], v[146:149], v[130:133]
	v_mfma_f32_16x16x32_bf16 v[150:153], v[6:9], v[146:149], v[126:129]
	v_mfma_f32_16x16x32_bf16 v[146:149], v[2:5], v[146:149], v[122:125]
	s_nop 2
	ds_read_b128 v[122:125], v0 offset:34816
	s_waitcnt lgkmcnt(0)
	v_mfma_f32_16x16x32_bf16 v[164:167], v[2:5], v[122:125], v[102:105]
	s_nop 2
	ds_read_b128 v[102:105], v0 offset:36864
	s_waitcnt lgkmcnt(0)
	v_mfma_f32_16x16x32_bf16 v[176:179], v[14:17], v[102:105], v[94:97]
	s_nop 2
	ds_read_b128 v[94:97], v0 offset:38912
	s_waitcnt lgkmcnt(0)
	v_mfma_f32_16x16x32_bf16 v[74:77], v[10:13], v[94:97], v[74:77]
	v_mfma_f32_16x16x32_bf16 v[70:73], v[14:17], v[94:97], v[70:73]
	v_mfma_f32_16x16x32_bf16 v[62:65], v[6:9], v[94:97], v[62:65]
	v_mfma_f32_16x16x32_bf16 v[66:69], v[2:5], v[94:97], v[66:69]
	ds_read_b128 v[94:97], v0 offset:40960
	s_waitcnt lgkmcnt(0)
	v_mfma_f32_16x16x32_bf16 v[190:193], v[2:5], v[94:97], v[54:57]
	s_nop 2
	ds_read_b128 v[54:57], v0 offset:43008
	s_waitcnt lgkmcnt(0)
	v_mfma_f32_16x16x32_bf16 v[194:197], v[2:5], v[54:57], v[42:45]
	s_nop 2
	ds_read_b128 v[42:45], v0 offset:45056
	s_waitcnt lgkmcnt(0)
	v_mfma_f32_16x16x32_bf16 v[226:229], v[6:9], v[42:45], v[30:33]
	s_nop 2
	ds_read_b128 v[30:33], v0 offset:47104
	v_add_u32_e32 v0, 32, v171
	v_mfma_f32_16x16x32_bf16 v[114:117], v[10:13], v[122:125], v[114:117]
	v_mfma_f32_16x16x32_bf16 v[154:157], v[14:17], v[122:125], v[110:113]
	v_mfma_f32_16x16x32_bf16 v[172:175], v[10:13], v[102:105], v[98:101]
	v_mfma_f32_16x16x32_bf16 v[46:49], v[10:13], v[94:97], v[46:49]
	v_mfma_f32_16x16x32_bf16 v[50:53], v[14:17], v[94:97], v[50:53]
	v_mfma_f32_16x16x32_bf16 v[26:29], v[10:13], v[54:57], v[26:29]
	v_mfma_f32_16x16x32_bf16 v[22:25], v[14:17], v[54:57], v[22:25]
	v_mfma_f32_16x16x32_bf16 v[198:201], v[10:13], v[42:45], v[34:37]
	v_mfma_f32_16x16x32_bf16 v[202:205], v[14:17], v[42:45], v[38:41]
	s_waitcnt lgkmcnt(0)
; #define MFMA16(a, b, c) __builtin_amdgcn_mfma_f32_16x16x32_bf16((a), (b), (c), 0, 0, 0)
; template <class Epi>
; DEVI void gemm_tile256b(const bf16_t* __restrict__ A, int lda, const bf16_t* __restrict__ Bt, int K,
;                         int m0, int n0, char* smem, Epi epi) {
;     ...
;         for (int ni = 0; ni < 4; ++ni) acc[mi][ni] = MFMA16(b1[ni], af[mi], acc[mi][ni]);
;     }
;     if (more) {
;       char* nb = smem + ((kt + 1) & 1) * 32768 + lds_w;
; #pragma unroll
;       for (int i = 0; i < 8; ++i) *(u32x4*)(nb + i * 4096) = ra[i];
;     }
;     __syncthreads();
;   }
; #pragma unroll
;   for (int mi = 0; mi < 8; ++mi)
; #pragma unroll
;     for (int ni = 0; ni < 4; ++ni)
;       epi(m0 + wm * 128 + mi * 16 + l15, n0 + wn * 64 + ni * 16 + quad * 4, acc[mi][ni]);
;   DEVI void operator()(int m, int n, f32x4 v) const {
;     if (m >= L) return;
;     float a = fmaxf(v[0], 0.f), b = fmaxf(v[1], 0.f), c = fmaxf(v[2], 0.f), d = fmaxf(v[3], 0.f);
;     *(u32x2*)(hid + (size_t)m * 4096 + n) = u32x2{pack2(a * a, b * b), pack2(c * c, d * d)};
;   }
	v_mfma_f32_16x16x32_bf16 v[10:13], v[10:13], v[30:33], v[138:141]
	v_mfma_f32_16x16x32_bf16 v[138:141], v[14:17], v[30:33], v[118:121]
	v_add_co_u32_e32 v14, vcc, s1, v162
	s_mov_b32 s1, 0xf000
	s_nop 0
	v_addc_co_u32_e32 v15, vcc, 0, v163, vcc
	global_load_dwordx4 v[14:17], v[14:15], off offset:3072
	v_mfma_f32_16x16x32_bf16 v[158:161], v[6:9], v[122:125], v[106:109]
	v_add_co_u32_e32 v34, vcc, s1, v162
	s_mov_b32 s1, 0x17000
	v_mfma_f32_16x16x32_bf16 v[86:89], v[6:9], v[102:105], v[86:89]
	v_addc_co_u32_e32 v35, vcc, 0, v163, vcc
	global_load_dwordx4 v[230:233], v[34:35], off offset:3072
	v_mfma_f32_16x16x32_bf16 v[82:85], v[2:5], v[102:105], v[82:85]
	v_add_co_u32_e32 v34, vcc, s1, v162
	s_mov_b32 s1, 0x1f000
	v_mfma_f32_16x16x32_bf16 v[180:183], v[6:9], v[94:97], v[58:61]
	v_addc_co_u32_e32 v35, vcc, 0, v163, vcc
	v_mfma_f32_16x16x32_bf16 v[18:21], v[6:9], v[54:57], v[18:21]
	v_mfma_f32_16x16x32_bf16 v[142:145], v[2:5], v[42:45], v[142:145]
	v_mfma_f32_16x16x32_bf16 v[6:9], v[6:9], v[30:33], v[90:93]
	v_mfma_f32_16x16x32_bf16 v[2:5], v[2:5], v[30:33], v[78:81]
	ds_read_b128 v[30:33], v0 offset:32768
	s_waitcnt vmcnt(1) lgkmcnt(0)
	v_mfma_f32_16x16x32_bf16 v[126:129], v[14:17], v[30:33], v[134:137]
	s_nop 2
	global_load_dwordx4 v[134:137], v[34:35], off offset:3072
	v_add_co_u32_e32 v34, vcc, s1, v162
	s_waitcnt vmcnt(1)
	v_mfma_f32_16x16x32_bf16 v[122:125], v[230:233], v[30:33], v[130:133]
	v_addc_co_u32_e32 v35, vcc, 0, v163, vcc
	s_nop 1
	v_lshl_or_b32 v130, v169, 2, v170
	s_waitcnt vmcnt(0)
	v_mfma_f32_16x16x32_bf16 v[118:121], v[134:137], v[30:33], v[150:153]
	s_nop 2
	global_load_dwordx4 v[150:153], v[34:35], off offset:3072
	v_ashrrev_i32_e32 v131, 31, v130
	s_waitcnt vmcnt(0)
	v_mfma_f32_16x16x32_bf16 v[110:113], v[150:153], v[30:33], v[146:149]
	ds_read_b128 v[30:33], v0 offset:34816
	s_waitcnt lgkmcnt(0)
	v_mfma_f32_16x16x32_bf16 v[114:117], v[14:17], v[30:33], v[114:117]
	v_mfma_f32_16x16x32_bf16 v[106:109], v[230:233], v[30:33], v[154:157]
	v_mfma_f32_16x16x32_bf16 v[102:105], v[134:137], v[30:33], v[158:161]
	v_mfma_f32_16x16x32_bf16 v[98:101], v[150:153], v[30:33], v[164:167]
	ds_read_b128 v[30:33], v0 offset:36864
	s_waitcnt lgkmcnt(0)
	v_mfma_f32_16x16x32_bf16 v[94:97], v[14:17], v[30:33], v[172:175]
	v_mfma_f32_16x16x32_bf16 v[90:93], v[230:233], v[30:33], v[176:179]
	v_mfma_f32_16x16x32_bf16 v[86:89], v[134:137], v[30:33], v[86:89]
	v_mfma_f32_16x16x32_bf16 v[82:85], v[150:153], v[30:33], v[82:85]
	ds_read_b128 v[30:33], v0 offset:38912
	s_waitcnt lgkmcnt(0)
	v_mfma_f32_16x16x32_bf16 v[78:81], v[14:17], v[30:33], v[74:77]
	v_mfma_f32_16x16x32_bf16 v[74:77], v[230:233], v[30:33], v[70:73]
	v_mfma_f32_16x16x32_bf16 v[70:73], v[134:137], v[30:33], v[62:65]
	v_mfma_f32_16x16x32_bf16 v[66:69], v[150:153], v[30:33], v[66:69]
	ds_read_b128 v[30:33], v0 offset:40960
	s_waitcnt lgkmcnt(0)
	v_mfma_f32_16x16x32_bf16 v[62:65], v[14:17], v[30:33], v[46:49]
	v_mfma_f32_16x16x32_bf16 v[58:61], v[230:233], v[30:33], v[50:53]
	v_mfma_f32_16x16x32_bf16 v[54:57], v[134:137], v[30:33], v[180:183]
	v_mfma_f32_16x16x32_bf16 v[50:53], v[150:153], v[30:33], v[190:193]
	ds_read_b128 v[30:33], v0 offset:43008
	s_waitcnt lgkmcnt(0)
	v_mfma_f32_16x16x32_bf16 v[38:41], v[134:137], v[30:33], v[18:21]
	s_nop 2
	ds_read_b128 v[18:21], v0 offset:45056
	v_mfma_f32_16x16x32_bf16 v[46:49], v[14:17], v[30:33], v[26:29]
	v_mfma_f32_16x16x32_bf16 v[42:45], v[230:233], v[30:33], v[22:25]
	v_mfma_f32_16x16x32_bf16 v[34:37], v[150:153], v[30:33], v[194:197]
	s_waitcnt lgkmcnt(0)
	v_mfma_f32_16x16x32_bf16 v[30:33], v[14:17], v[18:21], v[198:201]
	v_mfma_f32_16x16x32_bf16 v[26:29], v[230:233], v[18:21], v[202:205]
	v_mfma_f32_16x16x32_bf16 v[22:25], v[134:137], v[18:21], v[226:229]
	v_mfma_f32_16x16x32_bf16 v[18:21], v[150:153], v[18:21], v[142:145]
	s_nop 2
	ds_read_b128 v[142:145], v0 offset:47104
	s_waitcnt lgkmcnt(0)
	v_mfma_f32_16x16x32_bf16 v[14:17], v[14:17], v[142:145], v[10:13]
	v_and_b32_e32 v0, 0xffffff80, v168
	v_add_u32_e32 v0, s0, v0
	v_and_or_b32 v132, v168, 15, v0
	v_mfma_f32_16x16x32_bf16 v[10:13], v[230:233], v[142:145], v[138:141]
	s_movk_i32 s0, 0x4010
	v_cmp_gt_i32_e32 vcc, s0, v132
	v_mfma_f32_16x16x32_bf16 v[6:9], v[134:137], v[142:145], v[6:9]
	s_barrier
	v_mfma_f32_16x16x32_bf16 v[2:5], v[150:153], v[142:145], v[2:5]
	s_and_saveexec_b64 s[0:1], vcc
	s_cbranch_execz .LBB0_1876
	v_max_f32_e32 v0, v126, v126
	v_max_f32_e32 v126, 0, v0
	v_max_f32_e32 v0, v127, v127
	v_max_f32_e32 v127, 0, v0
	v_max_f32_e32 v0, v128, v128
	v_max_f32_e32 v128, 0, v0
	v_max_f32_e32 v0, v129, v129
	v_max_f32_e32 v129, 0, v0
	v_max_f32_e32 v0, v122, v122
	v_max_f32_e32 v122, 0, v0
	v_max_f32_e32 v0, v123, v123
	v_max_f32_e32 v123, 0, v0
	v_max_f32_e32 v0, v124, v124
	v_max_f32_e32 v124, 0, v0
	v_max_f32_e32 v0, v125, v125
	v_max_f32_e32 v125, 0, v0
	v_max_f32_e32 v0, v118, v118
	v_max_f32_e32 v118, 0, v0
	v_max_f32_e32 v0, v119, v119
	v_max_f32_e32 v119, 0, v0
	v_max_f32_e32 v0, v120, v120
	v_max_f32_e32 v120, 0, v0
	v_max_f32_e32 v0, v121, v121
	v_max_f32_e32 v121, 0, v0
	v_max_f32_e32 v0, v110, v110
	v_max_f32_e32 v110, 0, v0
	v_max_f32_e32 v0, v111, v111
	v_max_f32_e32 v111, 0, v0
	v_max_f32_e32 v0, v112, v112
	v_ashrrev_i32_e32 v133, 31, v132
	v_max_f32_e32 v112, 0, v0
	v_max_f32_e32 v0, v113, v113
	v_lshlrev_b64 v[134:135], 13, v[132:133]
	v_max_f32_e32 v113, 0, v0
	v_lshl_add_u64 v[134:135], s[30:31], 0, v[134:135]
	v_pk_mul_f32 v[126:127], v[126:127], v[126:127]
	v_pk_mul_f32 v[128:129], v[128:129], v[128:129]
	v_pk_mul_f32 v[122:123], v[122:123], v[122:123]
	v_pk_mul_f32 v[124:125], v[124:125], v[124:125]
	v_pk_mul_f32 v[118:119], v[118:119], v[118:119]
	v_pk_mul_f32 v[120:121], v[120:121], v[120:121]
	v_pk_mul_f32 v[110:111], v[110:111], v[110:111]
	v_pk_mul_f32 v[112:113], v[112:113], v[112:113]
	v_cvt_pk_bf16_f32 v126, v126, v127
	v_cvt_pk_bf16_f32 v127, v128, v129
	v_lshl_add_u64 v[234:235], v[130:131], 1, v[134:135]
	v_lshl_add_u64 v[234:235], v[234:235], 0, v[236:237]
	v_cvt_pk_bf16_f32 v128, v122, v123
	v_cvt_pk_bf16_f32 v129, v124, v125
	v_cvt_pk_bf16_f32 v118, v118, v119
	v_cvt_pk_bf16_f32 v119, v120, v121
	v_cvt_pk_bf16_f32 v120, v110, v111
	v_cvt_pk_bf16_f32 v121, v112, v113
	s_nop 1
	v_permlane16_swap_b32_e32 v126, v128
	v_permlane16_swap_b32_e32 v127, v129
	v_permlane16_swap_b32_e32 v118, v120
	v_permlane16_swap_b32_e32 v119, v121
	global_store_dwordx4 v[234:235], v[126:129], off
	global_store_dwordx4 v[234:235], v[118:121], off offset:64
	s_nop 1
; template <class Epi>
; DEVI void gemm_tile256b(const bf16_t* __restrict__ A, int lda, const bf16_t* __restrict__ Bt, int K,
;                         int m0, int n0, char* smem, Epi epi) {
;     ...
; #pragma unroll
;   for (int mi = 0; mi < 8; ++mi)
; #pragma unroll
;     for (int ni = 0; ni < 4; ++ni)
;       epi(m0 + wm * 128 + mi * 16 + l15, n0 + wn * 64 + ni * 16 + quad * 4, acc[mi][ni]);
;   DEVI void operator()(int m, int n, f32x4 v) const {
;     if (m >= L) return;
;     float a = fmaxf(v[0], 0.f), b = fmaxf(v[1], 0.f), c = fmaxf(v[2], 0.f), d = fmaxf(v[3], 0.f);
;     *(u32x2*)(hid + (size_t)m * 4096 + n) = u32x2{pack2(a * a, b * b), pack2(c * c, d * d)};
;   }
.LBB0_1876:
	s_or_b64 exec, exec, s[0:1]
	v_or_b32_e32 v110, 16, v132
	s_movk_i32 s0, 0x4010
	v_cmp_gt_i32_e32 vcc, s0, v110
	s_and_saveexec_b64 s[0:1], vcc
	s_cbranch_execz .LBB0_1878
	v_max_f32_e32 v0, v114, v114
	v_max_f32_e32 v112, 0, v0
	v_max_f32_e32 v0, v115, v115
	v_max_f32_e32 v113, 0, v0
	v_max_f32_e32 v0, v116, v116
	v_max_f32_e32 v114, 0, v0
	v_max_f32_e32 v0, v117, v117
	v_max_f32_e32 v115, 0, v0
	v_max_f32_e32 v0, v106, v106
	v_max_f32_e32 v106, 0, v0
	v_max_f32_e32 v0, v107, v107
	v_max_f32_e32 v107, 0, v0
	v_max_f32_e32 v0, v108, v108
	v_max_f32_e32 v108, 0, v0
	v_max_f32_e32 v0, v109, v109
	v_max_f32_e32 v109, 0, v0
	v_max_f32_e32 v0, v102, v102
	v_max_f32_e32 v102, 0, v0
	v_max_f32_e32 v0, v103, v103
	v_max_f32_e32 v103, 0, v0
	v_max_f32_e32 v0, v104, v104
	v_max_f32_e32 v104, 0, v0
	v_max_f32_e32 v0, v105, v105
	v_max_f32_e32 v105, 0, v0
	v_max_f32_e32 v0, v98, v98
	v_max_f32_e32 v98, 0, v0
	v_max_f32_e32 v0, v99, v99
	v_max_f32_e32 v99, 0, v0
	v_max_f32_e32 v0, v100, v100
	v_ashrrev_i32_e32 v111, 31, v110
	v_max_f32_e32 v100, 0, v0
	v_max_f32_e32 v0, v101, v101
	v_lshlrev_b64 v[110:111], 13, v[110:111]
	v_max_f32_e32 v101, 0, v0
	v_lshl_add_u64 v[110:111], s[30:31], 0, v[110:111]
	v_pk_mul_f32 v[112:113], v[112:113], v[112:113]
	v_pk_mul_f32 v[114:115], v[114:115], v[114:115]
	v_pk_mul_f32 v[106:107], v[106:107], v[106:107]
	v_pk_mul_f32 v[108:109], v[108:109], v[108:109]
	v_pk_mul_f32 v[102:103], v[102:103], v[102:103]
	v_pk_mul_f32 v[104:105], v[104:105], v[104:105]
	v_pk_mul_f32 v[98:99], v[98:99], v[98:99]
	v_pk_mul_f32 v[100:101], v[100:101], v[100:101]
	v_cvt_pk_bf16_f32 v112, v112, v113
	v_cvt_pk_bf16_f32 v113, v114, v115
	v_lshl_add_u64 v[234:235], v[130:131], 1, v[110:111]
	v_lshl_add_u64 v[234:235], v[234:235], 0, v[236:237]
	v_cvt_pk_bf16_f32 v114, v106, v107
	v_cvt_pk_bf16_f32 v115, v108, v109
	v_cvt_pk_bf16_f32 v102, v102, v103
	v_cvt_pk_bf16_f32 v103, v104, v105
	v_cvt_pk_bf16_f32 v104, v98, v99
	v_cvt_pk_bf16_f32 v105, v100, v101
	s_nop 1
	v_permlane16_swap_b32_e32 v112, v114
	v_permlane16_swap_b32_e32 v113, v115
	v_permlane16_swap_b32_e32 v102, v104
	v_permlane16_swap_b32_e32 v103, v105
	global_store_dwordx4 v[234:235], v[112:115], off
	global_store_dwordx4 v[234:235], v[102:105], off offset:64
	s_nop 1
.LBB0_1878:
	s_or_b64 exec, exec, s[0:1]
	v_or_b32_e32 v98, 32, v132
	s_movk_i32 s0, 0x4010
	v_cmp_gt_i32_e32 vcc, s0, v98
	s_and_saveexec_b64 s[0:1], vcc
	s_cbranch_execz .LBB0_1880
	v_max_f32_e32 v0, v94, v94
	v_max_f32_e32 v94, 0, v0
	v_max_f32_e32 v0, v95, v95
	v_max_f32_e32 v95, 0, v0
	v_max_f32_e32 v0, v96, v96
	v_max_f32_e32 v96, 0, v0
	v_max_f32_e32 v0, v97, v97
	v_max_f32_e32 v97, 0, v0
	v_max_f32_e32 v0, v90, v90
	v_max_f32_e32 v90, 0, v0
	v_max_f32_e32 v0, v91, v91
	v_max_f32_e32 v91, 0, v0
	v_max_f32_e32 v0, v92, v92
	v_max_f32_e32 v92, 0, v0
	v_max_f32_e32 v0, v93, v93
	v_max_f32_e32 v93, 0, v0
	v_max_f32_e32 v0, v86, v86
	v_max_f32_e32 v86, 0, v0
	v_max_f32_e32 v0, v87, v87
	v_max_f32_e32 v87, 0, v0
	v_max_f32_e32 v0, v88, v88
	v_max_f32_e32 v88, 0, v0
	v_max_f32_e32 v0, v89, v89
	v_max_f32_e32 v89, 0, v0
	v_max_f32_e32 v0, v82, v82
	v_max_f32_e32 v82, 0, v0
	v_max_f32_e32 v0, v83, v83
	v_max_f32_e32 v83, 0, v0
	v_max_f32_e32 v0, v84, v84
	v_ashrrev_i32_e32 v99, 31, v98
	v_max_f32_e32 v84, 0, v0
	v_max_f32_e32 v0, v85, v85
	v_lshlrev_b64 v[98:99], 13, v[98:99]
	v_max_f32_e32 v85, 0, v0
	v_lshl_add_u64 v[98:99], s[30:31], 0, v[98:99]
	v_pk_mul_f32 v[94:95], v[94:95], v[94:95]
	v_pk_mul_f32 v[96:97], v[96:97], v[96:97]
	v_pk_mul_f32 v[90:91], v[90:91], v[90:91]
	v_pk_mul_f32 v[92:93], v[92:93], v[92:93]
	v_pk_mul_f32 v[86:87], v[86:87], v[86:87]
	v_pk_mul_f32 v[88:89], v[88:89], v[88:89]
	v_pk_mul_f32 v[82:83], v[82:83], v[82:83]
	v_pk_mul_f32 v[84:85], v[84:85], v[84:85]
	v_cvt_pk_bf16_f32 v94, v94, v95
	v_cvt_pk_bf16_f32 v95, v96, v97
	v_lshl_add_u64 v[234:235], v[130:131], 1, v[98:99]
	v_lshl_add_u64 v[234:235], v[234:235], 0, v[236:237]
	v_cvt_pk_bf16_f32 v96, v90, v91
	v_cvt_pk_bf16_f32 v97, v92, v93
	v_cvt_pk_bf16_f32 v86, v86, v87
	v_cvt_pk_bf16_f32 v87, v88, v89
	v_cvt_pk_bf16_f32 v88, v82, v83
	v_cvt_pk_bf16_f32 v89, v84, v85
	s_nop 1
	v_permlane16_swap_b32_e32 v94, v96
	v_permlane16_swap_b32_e32 v95, v97
	v_permlane16_swap_b32_e32 v86, v88
	v_permlane16_swap_b32_e32 v87, v89
	global_store_dwordx4 v[234:235], v[94:97], off
	global_store_dwordx4 v[234:235], v[86:89], off offset:64
	s_nop 1
.LBB0_1880:
	s_or_b64 exec, exec, s[0:1]
	v_or_b32_e32 v82, 48, v132
	s_movk_i32 s0, 0x4010
	v_cmp_gt_i32_e32 vcc, s0, v82
	s_and_saveexec_b64 s[0:1], vcc
	s_cbranch_execz .LBB0_1882
	v_max_f32_e32 v0, v78, v78
	v_max_f32_e32 v78, 0, v0
	v_max_f32_e32 v0, v79, v79
	v_max_f32_e32 v79, 0, v0
	v_max_f32_e32 v0, v80, v80
	v_max_f32_e32 v80, 0, v0
	v_max_f32_e32 v0, v81, v81
	v_max_f32_e32 v81, 0, v0
	v_max_f32_e32 v0, v74, v74
	v_max_f32_e32 v74, 0, v0
	v_max_f32_e32 v0, v75, v75
	v_max_f32_e32 v75, 0, v0
	v_max_f32_e32 v0, v76, v76
	v_max_f32_e32 v76, 0, v0
	v_max_f32_e32 v0, v77, v77
	v_max_f32_e32 v77, 0, v0
	v_max_f32_e32 v0, v70, v70
	v_max_f32_e32 v70, 0, v0
	v_max_f32_e32 v0, v71, v71
	v_max_f32_e32 v71, 0, v0
	v_max_f32_e32 v0, v72, v72
	v_max_f32_e32 v72, 0, v0
	v_max_f32_e32 v0, v73, v73
	v_max_f32_e32 v73, 0, v0
	v_max_f32_e32 v0, v66, v66
	v_max_f32_e32 v66, 0, v0
	v_max_f32_e32 v0, v67, v67
	v_max_f32_e32 v67, 0, v0
	v_max_f32_e32 v0, v68, v68
	v_ashrrev_i32_e32 v83, 31, v82
	v_max_f32_e32 v68, 0, v0
	v_max_f32_e32 v0, v69, v69
	v_lshlrev_b64 v[82:83], 13, v[82:83]
	v_max_f32_e32 v69, 0, v0
	v_lshl_add_u64 v[82:83], s[30:31], 0, v[82:83]
	v_pk_mul_f32 v[78:79], v[78:79], v[78:79]
	v_pk_mul_f32 v[80:81], v[80:81], v[80:81]
	v_pk_mul_f32 v[74:75], v[74:75], v[74:75]
	v_pk_mul_f32 v[76:77], v[76:77], v[76:77]
	v_pk_mul_f32 v[70:71], v[70:71], v[70:71]
	v_pk_mul_f32 v[72:73], v[72:73], v[72:73]
	v_pk_mul_f32 v[66:67], v[66:67], v[66:67]
	v_pk_mul_f32 v[68:69], v[68:69], v[68:69]
	v_cvt_pk_bf16_f32 v78, v78, v79
	v_cvt_pk_bf16_f32 v79, v80, v81
	v_lshl_add_u64 v[234:235], v[130:131], 1, v[82:83]
	v_lshl_add_u64 v[234:235], v[234:235], 0, v[236:237]
	v_cvt_pk_bf16_f32 v80, v74, v75
	v_cvt_pk_bf16_f32 v81, v76, v77
	v_cvt_pk_bf16_f32 v70, v70, v71
	v_cvt_pk_bf16_f32 v71, v72, v73
	v_cvt_pk_bf16_f32 v72, v66, v67
	v_cvt_pk_bf16_f32 v73, v68, v69
	s_nop 1
	v_permlane16_swap_b32_e32 v78, v80
	v_permlane16_swap_b32_e32 v79, v81
	v_permlane16_swap_b32_e32 v70, v72
	v_permlane16_swap_b32_e32 v71, v73
	global_store_dwordx4 v[234:235], v[78:81], off
	global_store_dwordx4 v[234:235], v[70:73], off offset:64
	s_nop 1
; template <class Epi>
; DEVI void gemm_tile256b(const bf16_t* __restrict__ A, int lda, const bf16_t* __restrict__ Bt, int K,
;                         int m0, int n0, char* smem, Epi epi) {
;     ...
; #pragma unroll
;   for (int mi = 0; mi < 8; ++mi)
; #pragma unroll
;     for (int ni = 0; ni < 4; ++ni)
;       epi(m0 + wm * 128 + mi * 16 + l15, n0 + wn * 64 + ni * 16 + quad * 4, acc[mi][ni]);
;   DEVI void operator()(int m, int n, f32x4 v) const {
;     if (m >= L) return;
;     float a = fmaxf(v[0], 0.f), b = fmaxf(v[1], 0.f), c = fmaxf(v[2], 0.f), d = fmaxf(v[3], 0.f);
;     *(u32x2*)(hid + (size_t)m * 4096 + n) = u32x2{pack2(a * a, b * b), pack2(c * c, d * d)};
;   }
.LBB0_1882:
	s_or_b64 exec, exec, s[0:1]
	v_or_b32_e32 v66, 64, v132
	s_movk_i32 s0, 0x4010
	v_cmp_gt_i32_e32 vcc, s0, v66
	s_and_saveexec_b64 s[0:1], vcc
	s_cbranch_execz .LBB0_1884
	v_max_f32_e32 v0, v62, v62
	v_max_f32_e32 v62, 0, v0
	v_max_f32_e32 v0, v63, v63
	v_max_f32_e32 v63, 0, v0
	v_max_f32_e32 v0, v64, v64
	v_max_f32_e32 v64, 0, v0
	v_max_f32_e32 v0, v65, v65
	v_max_f32_e32 v65, 0, v0
	v_max_f32_e32 v0, v58, v58
	v_max_f32_e32 v58, 0, v0
	v_max_f32_e32 v0, v59, v59
	v_max_f32_e32 v59, 0, v0
	v_max_f32_e32 v0, v60, v60
	v_max_f32_e32 v60, 0, v0
	v_max_f32_e32 v0, v61, v61
	v_max_f32_e32 v61, 0, v0
	v_max_f32_e32 v0, v54, v54
	v_max_f32_e32 v54, 0, v0
	v_max_f32_e32 v0, v55, v55
	v_max_f32_e32 v55, 0, v0
	v_max_f32_e32 v0, v56, v56
	v_max_f32_e32 v56, 0, v0
	v_max_f32_e32 v0, v57, v57
	v_max_f32_e32 v57, 0, v0
	v_max_f32_e32 v0, v50, v50
	v_max_f32_e32 v50, 0, v0
	v_max_f32_e32 v0, v51, v51
	v_max_f32_e32 v51, 0, v0
	v_max_f32_e32 v0, v52, v52
	v_ashrrev_i32_e32 v67, 31, v66
	v_max_f32_e32 v52, 0, v0
	v_max_f32_e32 v0, v53, v53
	v_lshlrev_b64 v[66:67], 13, v[66:67]
	v_max_f32_e32 v53, 0, v0
	v_lshl_add_u64 v[66:67], s[30:31], 0, v[66:67]
	v_pk_mul_f32 v[62:63], v[62:63], v[62:63]
	v_pk_mul_f32 v[64:65], v[64:65], v[64:65]
	v_pk_mul_f32 v[58:59], v[58:59], v[58:59]
	v_pk_mul_f32 v[60:61], v[60:61], v[60:61]
	v_pk_mul_f32 v[54:55], v[54:55], v[54:55]
	v_pk_mul_f32 v[56:57], v[56:57], v[56:57]
	v_pk_mul_f32 v[50:51], v[50:51], v[50:51]
	v_pk_mul_f32 v[52:53], v[52:53], v[52:53]
	v_cvt_pk_bf16_f32 v62, v62, v63
	v_cvt_pk_bf16_f32 v63, v64, v65
	v_lshl_add_u64 v[234:235], v[130:131], 1, v[66:67]
	v_lshl_add_u64 v[234:235], v[234:235], 0, v[236:237]
	v_cvt_pk_bf16_f32 v64, v58, v59
	v_cvt_pk_bf16_f32 v65, v60, v61
	v_cvt_pk_bf16_f32 v54, v54, v55
	v_cvt_pk_bf16_f32 v55, v56, v57
	v_cvt_pk_bf16_f32 v56, v50, v51
	v_cvt_pk_bf16_f32 v57, v52, v53
	s_nop 1
	v_permlane16_swap_b32_e32 v62, v64
	v_permlane16_swap_b32_e32 v63, v65
	v_permlane16_swap_b32_e32 v54, v56
	v_permlane16_swap_b32_e32 v55, v57
	global_store_dwordx4 v[234:235], v[62:65], off
	global_store_dwordx4 v[234:235], v[54:57], off offset:64
	s_nop 1
.LBB0_1884:
	s_or_b64 exec, exec, s[0:1]
	v_or_b32_e32 v50, 0x50, v132
	s_movk_i32 s0, 0x4010
	v_cmp_gt_i32_e32 vcc, s0, v50
	s_and_saveexec_b64 s[0:1], vcc
	s_cbranch_execz .LBB0_1886
	v_max_f32_e32 v0, v46, v46
	v_max_f32_e32 v46, 0, v0
	v_max_f32_e32 v0, v47, v47
	v_max_f32_e32 v47, 0, v0
	v_max_f32_e32 v0, v48, v48
	v_max_f32_e32 v48, 0, v0
	v_max_f32_e32 v0, v49, v49
	v_max_f32_e32 v49, 0, v0
	v_max_f32_e32 v0, v42, v42
	v_max_f32_e32 v42, 0, v0
	v_max_f32_e32 v0, v43, v43
	v_max_f32_e32 v43, 0, v0
	v_max_f32_e32 v0, v44, v44
	v_max_f32_e32 v44, 0, v0
	v_max_f32_e32 v0, v45, v45
	v_max_f32_e32 v45, 0, v0
	v_max_f32_e32 v0, v38, v38
	v_max_f32_e32 v38, 0, v0
	v_max_f32_e32 v0, v39, v39
	v_max_f32_e32 v39, 0, v0
	v_max_f32_e32 v0, v40, v40
	v_max_f32_e32 v40, 0, v0
	v_max_f32_e32 v0, v41, v41
	v_max_f32_e32 v41, 0, v0
	v_max_f32_e32 v0, v34, v34
	v_max_f32_e32 v34, 0, v0
	v_max_f32_e32 v0, v35, v35
	v_max_f32_e32 v35, 0, v0
	v_max_f32_e32 v0, v36, v36
	v_ashrrev_i32_e32 v51, 31, v50
	v_max_f32_e32 v36, 0, v0
	v_max_f32_e32 v0, v37, v37
	v_lshlrev_b64 v[50:51], 13, v[50:51]
	v_max_f32_e32 v37, 0, v0
	v_lshl_add_u64 v[50:51], s[30:31], 0, v[50:51]
	v_pk_mul_f32 v[46:47], v[46:47], v[46:47]
	v_pk_mul_f32 v[48:49], v[48:49], v[48:49]
	v_pk_mul_f32 v[42:43], v[42:43], v[42:43]
	v_pk_mul_f32 v[44:45], v[44:45], v[44:45]
	v_pk_mul_f32 v[38:39], v[38:39], v[38:39]
	v_pk_mul_f32 v[40:41], v[40:41], v[40:41]
	v_pk_mul_f32 v[34:35], v[34:35], v[34:35]
	v_pk_mul_f32 v[36:37], v[36:37], v[36:37]
	v_cvt_pk_bf16_f32 v46, v46, v47
	v_cvt_pk_bf16_f32 v47, v48, v49
	v_lshl_add_u64 v[234:235], v[130:131], 1, v[50:51]
	v_lshl_add_u64 v[234:235], v[234:235], 0, v[236:237]
	v_cvt_pk_bf16_f32 v48, v42, v43
	v_cvt_pk_bf16_f32 v49, v44, v45
	v_cvt_pk_bf16_f32 v38, v38, v39
	v_cvt_pk_bf16_f32 v39, v40, v41
	v_cvt_pk_bf16_f32 v40, v34, v35
	v_cvt_pk_bf16_f32 v41, v36, v37
	s_nop 1
	v_permlane16_swap_b32_e32 v46, v48
	v_permlane16_swap_b32_e32 v47, v49
	v_permlane16_swap_b32_e32 v38, v40
	v_permlane16_swap_b32_e32 v39, v41
	global_store_dwordx4 v[234:235], v[46:49], off
	global_store_dwordx4 v[234:235], v[38:41], off offset:64
	s_nop 1
; template <class Epi>
; DEVI void gemm_tile256b(const bf16_t* __restrict__ A, int lda, const bf16_t* __restrict__ Bt, int K,
;                         int m0, int n0, char* smem, Epi epi) {
;     ...
; #pragma unroll
;   for (int mi = 0; mi < 8; ++mi)
; #pragma unroll
;     for (int ni = 0; ni < 4; ++ni)
;       epi(m0 + wm * 128 + mi * 16 + l15, n0 + wn * 64 + ni * 16 + quad * 4, acc[mi][ni]);
;   DEVI void operator()(int m, int n, f32x4 v) const {
;     if (m >= L) return;
;     float a = fmaxf(v[0], 0.f), b = fmaxf(v[1], 0.f), c = fmaxf(v[2], 0.f), d = fmaxf(v[3], 0.f);
;     *(u32x2*)(hid + (size_t)m * 4096 + n) = u32x2{pack2(a * a, b * b), pack2(c * c, d * d)};
;   }
.LBB0_1886:
	s_or_b64 exec, exec, s[0:1]
	v_or_b32_e32 v34, 0x60, v132
	s_movk_i32 s0, 0x4010
	v_cmp_gt_i32_e32 vcc, s0, v34
	s_and_saveexec_b64 s[0:1], vcc
	s_cbranch_execz .LBB0_1888
	v_max_f32_e32 v0, v30, v30
	v_max_f32_e32 v30, 0, v0
	v_max_f32_e32 v0, v31, v31
	v_max_f32_e32 v31, 0, v0
	v_max_f32_e32 v0, v32, v32
	v_max_f32_e32 v32, 0, v0
	v_max_f32_e32 v0, v33, v33
	v_max_f32_e32 v33, 0, v0
	v_max_f32_e32 v0, v26, v26
	v_max_f32_e32 v26, 0, v0
	v_max_f32_e32 v0, v27, v27
	v_max_f32_e32 v27, 0, v0
	v_max_f32_e32 v0, v28, v28
	v_max_f32_e32 v28, 0, v0
	v_max_f32_e32 v0, v29, v29
	v_max_f32_e32 v29, 0, v0
	v_max_f32_e32 v0, v22, v22
	v_max_f32_e32 v22, 0, v0
	v_max_f32_e32 v0, v23, v23
	v_max_f32_e32 v23, 0, v0
	v_max_f32_e32 v0, v24, v24
	v_max_f32_e32 v24, 0, v0
	v_max_f32_e32 v0, v25, v25
	v_max_f32_e32 v25, 0, v0
	v_max_f32_e32 v0, v18, v18
	v_max_f32_e32 v18, 0, v0
	v_max_f32_e32 v0, v19, v19
	v_max_f32_e32 v19, 0, v0
	v_max_f32_e32 v0, v20, v20
	v_ashrrev_i32_e32 v35, 31, v34
	v_max_f32_e32 v20, 0, v0
	v_max_f32_e32 v0, v21, v21
	v_lshlrev_b64 v[34:35], 13, v[34:35]
	v_max_f32_e32 v21, 0, v0
	v_lshl_add_u64 v[34:35], s[30:31], 0, v[34:35]
	v_pk_mul_f32 v[30:31], v[30:31], v[30:31]
	v_pk_mul_f32 v[32:33], v[32:33], v[32:33]
	v_pk_mul_f32 v[26:27], v[26:27], v[26:27]
	v_pk_mul_f32 v[28:29], v[28:29], v[28:29]
	v_pk_mul_f32 v[22:23], v[22:23], v[22:23]
	v_pk_mul_f32 v[24:25], v[24:25], v[24:25]
	v_pk_mul_f32 v[18:19], v[18:19], v[18:19]
	v_pk_mul_f32 v[20:21], v[20:21], v[20:21]
	v_cvt_pk_bf16_f32 v30, v30, v31
	v_cvt_pk_bf16_f32 v31, v32, v33
	v_lshl_add_u64 v[234:235], v[130:131], 1, v[34:35]
	v_lshl_add_u64 v[234:235], v[234:235], 0, v[236:237]
	v_cvt_pk_bf16_f32 v32, v26, v27
	v_cvt_pk_bf16_f32 v33, v28, v29
	v_cvt_pk_bf16_f32 v22, v22, v23
	v_cvt_pk_bf16_f32 v23, v24, v25
	v_cvt_pk_bf16_f32 v24, v18, v19
	v_cvt_pk_bf16_f32 v25, v20, v21
	s_nop 1
	v_permlane16_swap_b32_e32 v30, v32
	v_permlane16_swap_b32_e32 v31, v33
	v_permlane16_swap_b32_e32 v22, v24
	v_permlane16_swap_b32_e32 v23, v25
	global_store_dwordx4 v[234:235], v[30:33], off
	global_store_dwordx4 v[234:235], v[22:25], off offset:64
	s_nop 1
.LBB0_1888:
	s_or_b64 exec, exec, s[0:1]
	v_or_b32_e32 v18, 0x70, v132
	s_movk_i32 s0, 0x4010
	v_cmp_gt_i32_e32 vcc, s0, v18
	s_and_saveexec_b64 s[0:1], vcc
	s_cbranch_execz .LBB0_1861
	v_max_f32_e32 v0, v14, v14
	v_max_f32_e32 v14, 0, v0
	v_max_f32_e32 v0, v15, v15
	v_max_f32_e32 v15, 0, v0
	v_max_f32_e32 v0, v16, v16
	v_max_f32_e32 v16, 0, v0
	v_max_f32_e32 v0, v17, v17
	v_max_f32_e32 v17, 0, v0
	v_max_f32_e32 v0, v10, v10
	v_max_f32_e32 v10, 0, v0
	v_max_f32_e32 v0, v11, v11
	v_max_f32_e32 v11, 0, v0
	v_max_f32_e32 v0, v12, v12
	v_max_f32_e32 v12, 0, v0
	v_max_f32_e32 v0, v13, v13
	v_max_f32_e32 v13, 0, v0
	v_max_f32_e32 v0, v6, v6
	v_max_f32_e32 v6, 0, v0
	v_max_f32_e32 v0, v7, v7
	v_max_f32_e32 v7, 0, v0
	v_max_f32_e32 v0, v8, v8
	v_max_f32_e32 v8, 0, v0
	v_max_f32_e32 v0, v9, v9
	v_max_f32_e32 v9, 0, v0
	v_max_f32_e32 v0, v2, v2
	v_max_f32_e32 v2, 0, v0
	v_max_f32_e32 v0, v3, v3
	v_max_f32_e32 v3, 0, v0
	v_max_f32_e32 v0, v4, v4
	v_ashrrev_i32_e32 v19, 31, v18
	v_max_f32_e32 v4, 0, v0
	v_max_f32_e32 v0, v5, v5
	v_lshlrev_b64 v[18:19], 13, v[18:19]
	v_max_f32_e32 v5, 0, v0
	v_lshl_add_u64 v[18:19], s[30:31], 0, v[18:19]
	v_pk_mul_f32 v[14:15], v[14:15], v[14:15]
	v_pk_mul_f32 v[16:17], v[16:17], v[16:17]
	v_pk_mul_f32 v[10:11], v[10:11], v[10:11]
	v_pk_mul_f32 v[12:13], v[12:13], v[12:13]
	v_pk_mul_f32 v[6:7], v[6:7], v[6:7]
	v_pk_mul_f32 v[8:9], v[8:9], v[8:9]
	v_pk_mul_f32 v[2:3], v[2:3], v[2:3]
	v_pk_mul_f32 v[4:5], v[4:5], v[4:5]
	v_cvt_pk_bf16_f32 v14, v14, v15
	v_cvt_pk_bf16_f32 v15, v16, v17
	v_lshl_add_u64 v[234:235], v[130:131], 1, v[18:19]
	v_lshl_add_u64 v[234:235], v[234:235], 0, v[236:237]
	v_cvt_pk_bf16_f32 v16, v10, v11
	v_cvt_pk_bf16_f32 v17, v12, v13
	v_cvt_pk_bf16_f32 v6, v6, v7
	v_cvt_pk_bf16_f32 v7, v8, v9
	v_cvt_pk_bf16_f32 v8, v2, v3
	v_cvt_pk_bf16_f32 v9, v4, v5
	s_nop 1
	v_permlane16_swap_b32_e32 v14, v16
	v_permlane16_swap_b32_e32 v15, v17
	v_permlane16_swap_b32_e32 v6, v8
	v_permlane16_swap_b32_e32 v7, v9
	global_store_dwordx4 v[234:235], v[14:17], off
	global_store_dwordx4 v[234:235], v[6:9], off offset:64
	s_nop 1
	s_branch .LBB0_1861
